# stack: sc1 slot loads without acquire fence; 4/4 LDS-DMA rebalance and MFMA hoist in both K-loops; residual-stream stores issued before the publication wait; redundant mid-segment setprio pairs remove
# baseline (speedup 1.0000x reference)
; #define PG8_STAGE(bufoff, gbase, voff) do { _Pragma("unroll") for (int _i = 0; _i < 2; ++_i) \
;         __builtin_amdgcn_global_load_lds((const unsigned*)((const char*)(gbase) + (voff)[_i]), (PG8_LAS unsigned*)(lds + (bufoff) + ldsw + _i * 8192), 16, 0, 0); } while (0)
; #define PG8_LDA(dst, b, h) do { _Pragma("unroll") for (int m = 0; m < 4; ++m) _Pragma("unroll") for (int k = 0; k < 2; ++k) dst[m][k] = *(const PG8_LAS bf16x8*)(lds + PG8_SA(b, h) + aoff + m * 2048 + k * 1024); } while (0)
; #define PG8_LDB(dst, b, h) do { _Pragma("unroll") for (int n = 0; n < 2; ++n) _Pragma("unroll") for (int k = 0; k < 2; ++k) dst[n][k] = *(const PG8_LAS bf16x8*)(lds + PG8_SB(b, h) + boff + n * 2048 + k * 1024); } while (0)
; #define PG8_MMA(ai, bj, At, Bt) do { __builtin_amdgcn_s_setprio(1); _Pragma("unroll") for (int m = 0; m < 4; ++m) _Pragma("unroll") for (int n = 0; n < 2; ++n) _Pragma("unroll") for (int k = 0; k < 2; ++k) \
;         acc[ai][bj][m][n] = __builtin_amdgcn_mfma_f32_16x16x32_bf16(Bt[n][k], At[m][k], acc[ai][bj][m][n], 0, 0, 0); __builtin_amdgcn_s_setprio(0); } while (0)
; #define PG8_WAIT_V(n) asm volatile("s_waitcnt vmcnt(" #n ")" ::: "memory")
; #define PG8_WAIT_L(n) asm volatile("s_waitcnt lgkmcnt(" #n ")" ::: "memory")
; #define PG8_BAR __builtin_amdgcn_s_barrier()
; #define PG8_SCHED __builtin_amdgcn_sched_barrier(0)
; template <class Epi, class Sched, bool ALIGN_EPI = false>
; __device__ __forceinline__ void gemm_phase(PG8_LAS unsigned char* lds, const Gemm g, const Sched& S, const Epi& E, int tid_in) {
;     ...
;             PG8_LDB(B0, 0, 0); PG8_LDB(B1, 0, 1); PG8_SCHED; PG8_LDA(At, 0, 0); PG8_STAGE(PG8_SA(1, 1), a1 + hstepA, voffA);
;             PG8_WAIT_V(8); PG8_WAIT_L(0); PG8_BAR; PG8_MMA(0, 0, At, B0); PG8_MMA(0, 1, At, B1); PG8_BAR; PG8_SCHED;
;             PG8_LDA(At, 0, 1); PG8_STAGE(PG8_SB(0, 0), b2, voffB); PG8_STAGE(PG8_SB(0, 1), b2 + hstepB, voffB); PG8_STAGE(PG8_SA(0, 0), a2, voffA);
;             PG8_WAIT_V(8); PG8_WAIT_L(0); PG8_BAR; PG8_MMA(1, 0, At, B0); PG8_MMA(1, 1, At, B1); PG8_BAR; PG8_SCHED;
.LBB0_152:
	s_add_u32 s18, s14, s16
	s_addc_u32 s19, s15, s17
	s_add_u32 s18, s18, 0x100
	s_addc_u32 s19, s19, 0
	s_add_u32 s22, s49, s16
	s_addc_u32 s23, s50, s17
	s_cmpk_eq_i32 s16, 0x700
	s_cselect_b32 s21, s11, s19
	s_cselect_b32 s20, s10, s18
	s_cselect_b32 s19, s45, s23
	s_cselect_b32 s18, s46, s22
	s_add_i32 s22, 0, 0x10000
	v_add_u32_e32 v80, s22, v192
	s_add_i32 s52, 0, 0x14000
	ds_read_b128 v[132:135], v80
	ds_read_b128 v[136:139], v80 offset:1024
	ds_read_b128 v[140:143], v80 offset:2048
	ds_read_b128 v[144:147], v80 offset:3072
	v_add_u32_e32 v80, s52, v192
	ds_read_b128 v[148:151], v80
	ds_read_b128 v[152:155], v80 offset:1024
	ds_read_b128 v[156:159], v80 offset:2048
	ds_read_b128 v[160:163], v80 offset:3072
	v_lshl_add_u64 v[82:83], v[186:187], 0, s[16:17]
	s_add_i32 m0, s34, 0xc000
	ds_read_b128 v[164:167], v195
	ds_read_b128 v[168:171], v195 offset:1024
	ds_read_b128 v[196:199], v195 offset:2048
	ds_read_b128 v[200:203], v195 offset:3072
	ds_read_b128 v[204:207], v195 offset:4096
	ds_read_b128 v[208:211], v195 offset:5120
	ds_read_b128 v[212:215], v195 offset:6144
	ds_read_b128 v[216:219], v195 offset:7168
	v_lshl_add_u64 v[244:245], s[14:15], 0, v[178:179]
	v_lshl_add_u64 v[246:247], s[14:15], 0, v[174:175]
	v_lshl_add_u64 v[244:245], v[244:245], 0, s[16:17]
	v_lshl_add_u64 v[246:247], v[246:247], 0, s[16:17]
	v_lshl_add_u64 v[244:245], v[244:245], 0, s[96:97]
	s_mov_b32 m0, s40
	v_lshl_add_u64 v[246:247], v[246:247], 0, s[96:97]
	global_load_lds_dwordx4 v[244:245], off
	s_mov_b32 m0, s41
	s_nop 0
	global_load_lds_dwordx4 v[246:247], off
	s_add_i32 m0, s34, 0xc000
	s_nop 0
	global_load_lds_dwordx4 v[82:83], off
	v_lshl_add_u64 v[82:83], v[188:189], 0, s[16:17]
	s_add_i32 m0, s34, 0xe000
	s_nop 0
	global_load_lds_dwordx4 v[82:83], off
	s_waitcnt vmcnt(8)
	s_waitcnt lgkmcnt(0)
	v_mfma_f32_16x16x32_bf16 v[128:131], v[132:135], v[164:167], v[128:131]
	v_mfma_f32_16x16x32_bf16 v[124:127], v[140:143], v[164:167], v[124:127]
	s_barrier
	s_setprio 1
	s_waitcnt lgkmcnt(0)
	v_mfma_f32_16x16x32_bf16 v[112:115], v[132:135], v[196:199], v[112:115]
	v_mfma_f32_16x16x32_bf16 v[108:111], v[140:143], v[196:199], v[108:111]
	v_mfma_f32_16x16x32_bf16 v[96:99], v[132:135], v[204:207], v[96:99]
	v_mfma_f32_16x16x32_bf16 v[92:95], v[140:143], v[204:207], v[92:95]
	v_mfma_f32_16x16x32_bf16 v[76:79], v[132:135], v[212:215], v[76:79]
	v_mfma_f32_16x16x32_bf16 v[72:75], v[140:143], v[212:215], v[72:75]
	v_mfma_f32_16x16x32_bf16 v[128:131], v[136:139], v[168:171], v[128:131]
	v_mfma_f32_16x16x32_bf16 v[124:127], v[144:147], v[168:171], v[124:127]
	v_mfma_f32_16x16x32_bf16 v[112:115], v[136:139], v[200:203], v[112:115]
	v_mfma_f32_16x16x32_bf16 v[108:111], v[144:147], v[200:203], v[108:111]
	v_mfma_f32_16x16x32_bf16 v[96:99], v[136:139], v[208:211], v[96:99]
	v_mfma_f32_16x16x32_bf16 v[92:95], v[144:147], v[208:211], v[92:95]
	v_mfma_f32_16x16x32_bf16 v[76:79], v[136:139], v[216:219], v[76:79]
	v_mfma_f32_16x16x32_bf16 v[72:75], v[144:147], v[216:219], v[72:75]
	v_mfma_f32_16x16x32_bf16 v[120:123], v[148:151], v[164:167], v[120:123]
	v_mfma_f32_16x16x32_bf16 v[116:119], v[156:159], v[164:167], v[116:119]
	v_mfma_f32_16x16x32_bf16 v[104:107], v[148:151], v[196:199], v[104:107]
	v_mfma_f32_16x16x32_bf16 v[100:103], v[156:159], v[196:199], v[100:103]
	v_mfma_f32_16x16x32_bf16 v[88:91], v[148:151], v[204:207], v[88:91]
	v_mfma_f32_16x16x32_bf16 v[82:85], v[156:159], v[204:207], v[84:87]
	v_mfma_f32_16x16x32_bf16 v[68:71], v[148:151], v[212:215], v[68:71]
	v_mfma_f32_16x16x32_bf16 v[64:67], v[156:159], v[212:215], v[64:67]
	v_mfma_f32_16x16x32_bf16 v[120:123], v[152:155], v[168:171], v[120:123]
	v_mfma_f32_16x16x32_bf16 v[116:119], v[160:163], v[168:171], v[116:119]
	v_mfma_f32_16x16x32_bf16 v[104:107], v[152:155], v[200:203], v[104:107]
	v_mfma_f32_16x16x32_bf16 v[100:103], v[160:163], v[200:203], v[100:103]
	v_mfma_f32_16x16x32_bf16 v[88:91], v[152:155], v[208:211], v[88:91]
	v_mfma_f32_16x16x32_bf16 v[82:85], v[160:163], v[208:211], v[82:85]
	v_mfma_f32_16x16x32_bf16 v[68:71], v[152:155], v[216:219], v[68:71]
	v_mfma_f32_16x16x32_bf16 v[64:67], v[160:163], v[216:219], v[64:67]
	s_setprio 0
	s_barrier
	s_add_i32 s22, s22, s33
	v_lshl_add_u64 v[244:245], s[18:19], 0, v[176:177]
	s_mov_b32 m0, s22
	ds_read_b128 v[164:167], v195 offset:16384
	ds_read_b128 v[168:171], v195 offset:17408
	ds_read_b128 v[196:199], v195 offset:18432
	ds_read_b128 v[200:203], v195 offset:19456
	ds_read_b128 v[204:207], v195 offset:20480
	ds_read_b128 v[208:211], v195 offset:21504
	ds_read_b128 v[212:215], v195 offset:22528
	ds_read_b128 v[216:219], v195 offset:23552
	global_load_lds_dwordx4 v[244:245], off
	s_add_i32 m0, s22, 0x2000
	s_add_u32 s22, s18, 0x40000
	v_lshl_add_u64 v[246:247], s[18:19], 0, v[172:173]
	s_addc_u32 s23, s19, 0
	s_add_i32 s52, s52, s33
	global_load_lds_dwordx4 v[246:247], off
	v_lshl_add_u64 v[86:87], s[22:23], 0, v[176:177]
	s_mov_b32 m0, s52
	v_lshl_add_u64 v[248:249], s[20:21], 0, v[178:179]
	global_load_lds_dwordx4 v[86:87], off
	v_lshl_add_u64 v[86:87], s[22:23], 0, v[172:173]
	s_add_i32 m0, s52, 0x2000
	v_lshl_add_u64 v[228:229], s[20:21], 0, v[174:175]
	global_load_lds_dwordx4 v[86:87], off
	s_waitcnt vmcnt(6)
	s_waitcnt lgkmcnt(0)
	v_mfma_f32_16x16x32_bf16 v[60:63], v[132:135], v[164:167], v[60:63]
	v_mfma_f32_16x16x32_bf16 v[56:59], v[140:143], v[164:167], v[56:59]
	s_barrier
; #define PG8_STAGE(bufoff, gbase, voff) do { _Pragma("unroll") for (int _i = 0; _i < 2; ++_i) \
;         __builtin_amdgcn_global_load_lds((const unsigned*)((const char*)(gbase) + (voff)[_i]), (PG8_LAS unsigned*)(lds + (bufoff) + ldsw + _i * 8192), 16, 0, 0); } while (0)
; #define PG8_LDA(dst, b, h) do { _Pragma("unroll") for (int m = 0; m < 4; ++m) _Pragma("unroll") for (int k = 0; k < 2; ++k) dst[m][k] = *(const PG8_LAS bf16x8*)(lds + PG8_SA(b, h) + aoff + m * 2048 + k * 1024); } while (0)
; #define PG8_LDB(dst, b, h) do { _Pragma("unroll") for (int n = 0; n < 2; ++n) _Pragma("unroll") for (int k = 0; k < 2; ++k) dst[n][k] = *(const PG8_LAS bf16x8*)(lds + PG8_SB(b, h) + boff + n * 2048 + k * 1024); } while (0)
; #define PG8_MMA(ai, bj, At, Bt) do { __builtin_amdgcn_s_setprio(1); _Pragma("unroll") for (int m = 0; m < 4; ++m) _Pragma("unroll") for (int n = 0; n < 2; ++n) _Pragma("unroll") for (int k = 0; k < 2; ++k) \
;         acc[ai][bj][m][n] = __builtin_amdgcn_mfma_f32_16x16x32_bf16(Bt[n][k], At[m][k], acc[ai][bj][m][n], 0, 0, 0); __builtin_amdgcn_s_setprio(0); } while (0)
; #define PG8_WAIT_V(n) asm volatile("s_waitcnt vmcnt(" #n ")" ::: "memory")
; #define PG8_WAIT_L(n) asm volatile("s_waitcnt lgkmcnt(" #n ")" ::: "memory")
; #define PG8_BAR __builtin_amdgcn_s_barrier()
; #define PG8_SCHED __builtin_amdgcn_sched_barrier(0)
; template <class Epi, class Sched, bool ALIGN_EPI = false>
; __device__ __forceinline__ void gemm_phase(PG8_LAS unsigned char* lds, const Gemm g, const Sched& S, const Epi& E, int tid_in) {
;     ...
;             PG8_WAIT_V(8); PG8_WAIT_L(0); PG8_BAR; PG8_MMA(1, 0, At, B0); PG8_MMA(1, 1, At, B1); PG8_BAR; PG8_SCHED;
;             PG8_LDB(B0, 1, 0); PG8_LDB(B1, 1, 1); PG8_SCHED; PG8_LDA(At, 1, 0); PG8_STAGE(PG8_SA(0, 1), a2 + hstepA, voffA);
;             PG8_WAIT_V(8); PG8_WAIT_L(0); PG8_BAR; PG8_MMA(0, 0, At, B0); PG8_MMA(0, 1, At, B1); PG8_BAR; PG8_SCHED;
	s_setprio 1
	s_waitcnt lgkmcnt(0)
	v_mfma_f32_16x16x32_bf16 v[44:47], v[132:135], v[196:199], v[44:47]
	v_mfma_f32_16x16x32_bf16 v[40:43], v[140:143], v[196:199], v[40:43]
	v_mfma_f32_16x16x32_bf16 v[28:31], v[132:135], v[204:207], v[28:31]
	v_mfma_f32_16x16x32_bf16 v[24:27], v[140:143], v[204:207], v[24:27]
	v_mfma_f32_16x16x32_bf16 v[12:15], v[132:135], v[212:215], v[12:15]
	v_mfma_f32_16x16x32_bf16 v[8:11], v[140:143], v[212:215], v[8:11]
	v_mfma_f32_16x16x32_bf16 v[60:63], v[136:139], v[168:171], v[60:63]
	v_mfma_f32_16x16x32_bf16 v[56:59], v[144:147], v[168:171], v[56:59]
	v_mfma_f32_16x16x32_bf16 v[44:47], v[136:139], v[200:203], v[44:47]
	v_mfma_f32_16x16x32_bf16 v[40:43], v[144:147], v[200:203], v[40:43]
	v_mfma_f32_16x16x32_bf16 v[28:31], v[136:139], v[208:211], v[28:31]
	v_mfma_f32_16x16x32_bf16 v[24:27], v[144:147], v[208:211], v[24:27]
	v_mfma_f32_16x16x32_bf16 v[12:15], v[136:139], v[216:219], v[12:15]
	v_mfma_f32_16x16x32_bf16 v[8:11], v[144:147], v[216:219], v[8:11]
	v_mfma_f32_16x16x32_bf16 v[52:55], v[148:151], v[164:167], v[52:55]
	v_mfma_f32_16x16x32_bf16 v[48:51], v[156:159], v[164:167], v[48:51]
	v_mfma_f32_16x16x32_bf16 v[36:39], v[148:151], v[196:199], v[36:39]
	v_mfma_f32_16x16x32_bf16 v[32:35], v[156:159], v[196:199], v[32:35]
	v_mfma_f32_16x16x32_bf16 v[20:23], v[148:151], v[204:207], v[20:23]
	v_mfma_f32_16x16x32_bf16 v[16:19], v[156:159], v[204:207], v[16:19]
	v_mfma_f32_16x16x32_bf16 v[4:7], v[148:151], v[212:215], v[4:7]
	v_mfma_f32_16x16x32_bf16 v[0:3], v[156:159], v[212:215], v[0:3]
	v_mfma_f32_16x16x32_bf16 v[52:55], v[152:155], v[168:171], v[52:55]
	v_mfma_f32_16x16x32_bf16 v[48:51], v[160:163], v[168:171], v[48:51]
	v_mfma_f32_16x16x32_bf16 v[36:39], v[152:155], v[200:203], v[36:39]
	v_mfma_f32_16x16x32_bf16 v[32:35], v[160:163], v[200:203], v[32:35]
	v_mfma_f32_16x16x32_bf16 v[20:23], v[152:155], v[208:211], v[20:23]
	v_mfma_f32_16x16x32_bf16 v[16:19], v[160:163], v[208:211], v[16:19]
	v_mfma_f32_16x16x32_bf16 v[4:7], v[152:155], v[216:219], v[4:7]
	v_mfma_f32_16x16x32_bf16 v[0:3], v[160:163], v[216:219], v[0:3]
	s_setprio 0
	s_barrier
	s_add_i32 s22, 0, 0x18000
	v_add_u32_e32 v80, s22, v192
	s_add_i32 s23, 0, 0x1c000
	ds_read_b128 v[132:135], v80
	ds_read_b128 v[136:139], v80 offset:1024
	ds_read_b128 v[140:143], v80 offset:2048
	ds_read_b128 v[144:147], v80 offset:3072
	v_add_u32_e32 v80, s23, v192
	ds_read_b128 v[148:151], v80
	ds_read_b128 v[152:155], v80 offset:1024
	ds_read_b128 v[156:159], v80 offset:2048
	ds_read_b128 v[160:163], v80 offset:3072
	s_add_u32 s20, s20, 0xb0000
	s_addc_u32 s21, s21, 0
	s_mov_b32 m0, s34
	v_lshl_add_u64 v[86:87], s[20:21], 0, v[178:179]
	ds_read_b128 v[164:167], v195 offset:32768
	ds_read_b128 v[168:171], v195 offset:33792
	ds_read_b128 v[196:199], v195 offset:34816
	ds_read_b128 v[200:203], v195 offset:35840
	ds_read_b128 v[204:207], v195 offset:36864
	ds_read_b128 v[208:211], v195 offset:37888
	ds_read_b128 v[212:215], v195 offset:38912
	ds_read_b128 v[216:219], v195 offset:39936
	global_load_lds_dwordx4 v[248:249], off
	s_mov_b32 m0, s35
	s_nop 0
	global_load_lds_dwordx4 v[228:229], off
	s_mov_b32 m0, s36
	s_nop 0
	global_load_lds_dwordx4 v[86:87], off
	v_lshl_add_u64 v[86:87], s[20:21], 0, v[174:175]
	s_mov_b32 m0, s37
	s_nop 0
	global_load_lds_dwordx4 v[86:87], off
	s_waitcnt vmcnt(8)
	s_waitcnt lgkmcnt(0)
	v_mfma_f32_16x16x32_bf16 v[128:131], v[132:135], v[164:167], v[128:131]
	v_mfma_f32_16x16x32_bf16 v[124:127], v[140:143], v[164:167], v[124:127]
	s_barrier
; #define PG8_STAGE(bufoff, gbase, voff) do { _Pragma("unroll") for (int _i = 0; _i < 2; ++_i) \
;         __builtin_amdgcn_global_load_lds((const unsigned*)((const char*)(gbase) + (voff)[_i]), (PG8_LAS unsigned*)(lds + (bufoff) + ldsw + _i * 8192), 16, 0, 0); } while (0)
; #define PG8_LDA(dst, b, h) do { _Pragma("unroll") for (int m = 0; m < 4; ++m) _Pragma("unroll") for (int k = 0; k < 2; ++k) dst[m][k] = *(const PG8_LAS bf16x8*)(lds + PG8_SA(b, h) + aoff + m * 2048 + k * 1024); } while (0)
; #define PG8_MMA(ai, bj, At, Bt) do { __builtin_amdgcn_s_setprio(1); _Pragma("unroll") for (int m = 0; m < 4; ++m) _Pragma("unroll") for (int n = 0; n < 2; ++n) _Pragma("unroll") for (int k = 0; k < 2; ++k) \
;         acc[ai][bj][m][n] = __builtin_amdgcn_mfma_f32_16x16x32_bf16(Bt[n][k], At[m][k], acc[ai][bj][m][n], 0, 0, 0); __builtin_amdgcn_s_setprio(0); } while (0)
; #define PG8_WAIT_V(n) asm volatile("s_waitcnt vmcnt(" #n ")" ::: "memory")
; #define PG8_WAIT_L(n) asm volatile("s_waitcnt lgkmcnt(" #n ")" ::: "memory")
; #define PG8_BAR __builtin_amdgcn_s_barrier()
; #define PG8_SCHED __builtin_amdgcn_sched_barrier(0)
; template <class Epi, class Sched, bool ALIGN_EPI = false>
; __device__ __forceinline__ void gemm_phase(PG8_LAS unsigned char* lds, const Gemm g, const Sched& S, const Epi& E, int tid_in) {
;     ...
;             PG8_WAIT_V(8); PG8_WAIT_L(0); PG8_BAR; PG8_MMA(0, 0, At, B0); PG8_MMA(0, 1, At, B1); PG8_BAR; PG8_SCHED;
;             PG8_LDA(At, 1, 1); PG8_STAGE(PG8_SB(1, 0), b3, voffB); PG8_STAGE(PG8_SB(1, 1), b3 + hstepB, voffB); PG8_STAGE(PG8_SA(1, 0), a3, voffA);
;             PG8_WAIT_V(8); PG8_WAIT_L(0); PG8_BAR; PG8_MMA(1, 0, At, B0); PG8_MMA(1, 1, At, B1); PG8_BAR; PG8_SCHED;
;         }
	s_setprio 1
	s_waitcnt lgkmcnt(0)
	v_mfma_f32_16x16x32_bf16 v[112:115], v[132:135], v[196:199], v[112:115]
	v_mfma_f32_16x16x32_bf16 v[108:111], v[140:143], v[196:199], v[108:111]
	v_mfma_f32_16x16x32_bf16 v[96:99], v[132:135], v[204:207], v[96:99]
	v_mfma_f32_16x16x32_bf16 v[92:95], v[140:143], v[204:207], v[92:95]
	v_mfma_f32_16x16x32_bf16 v[76:79], v[132:135], v[212:215], v[76:79]
	v_mfma_f32_16x16x32_bf16 v[72:75], v[140:143], v[212:215], v[72:75]
	v_mfma_f32_16x16x32_bf16 v[128:131], v[136:139], v[168:171], v[128:131]
	v_mfma_f32_16x16x32_bf16 v[124:127], v[144:147], v[168:171], v[124:127]
	v_mfma_f32_16x16x32_bf16 v[112:115], v[136:139], v[200:203], v[112:115]
	v_mfma_f32_16x16x32_bf16 v[108:111], v[144:147], v[200:203], v[108:111]
	v_mfma_f32_16x16x32_bf16 v[96:99], v[136:139], v[208:211], v[96:99]
	v_mfma_f32_16x16x32_bf16 v[92:95], v[144:147], v[208:211], v[92:95]
	v_mfma_f32_16x16x32_bf16 v[76:79], v[136:139], v[216:219], v[76:79]
	v_mfma_f32_16x16x32_bf16 v[72:75], v[144:147], v[216:219], v[72:75]
	v_mfma_f32_16x16x32_bf16 v[120:123], v[148:151], v[164:167], v[120:123]
	v_mfma_f32_16x16x32_bf16 v[116:119], v[156:159], v[164:167], v[116:119]
	v_mfma_f32_16x16x32_bf16 v[104:107], v[148:151], v[196:199], v[104:107]
	v_mfma_f32_16x16x32_bf16 v[100:103], v[156:159], v[196:199], v[100:103]
	v_mfma_f32_16x16x32_bf16 v[86:89], v[148:151], v[204:207], v[88:91]
	v_mfma_f32_16x16x32_bf16 v[82:85], v[156:159], v[204:207], v[82:85]
	v_mfma_f32_16x16x32_bf16 v[68:71], v[148:151], v[212:215], v[68:71]
	v_mfma_f32_16x16x32_bf16 v[64:67], v[156:159], v[212:215], v[64:67]
	v_mfma_f32_16x16x32_bf16 v[120:123], v[152:155], v[168:171], v[120:123]
	v_mfma_f32_16x16x32_bf16 v[116:119], v[160:163], v[168:171], v[116:119]
	v_mfma_f32_16x16x32_bf16 v[104:107], v[152:155], v[200:203], v[104:107]
	v_mfma_f32_16x16x32_bf16 v[100:103], v[160:163], v[200:203], v[100:103]
	v_mfma_f32_16x16x32_bf16 v[88:91], v[152:155], v[208:211], v[86:89]
	v_mfma_f32_16x16x32_bf16 v[84:87], v[160:163], v[208:211], v[82:85]
	v_mfma_f32_16x16x32_bf16 v[68:71], v[152:155], v[216:219], v[68:71]
	v_mfma_f32_16x16x32_bf16 v[64:67], v[160:163], v[216:219], v[64:67]
	s_setprio 0
	s_barrier
	s_add_i32 s20, s22, s33
	v_lshl_add_u64 v[82:83], v[244:245], 0, s[96:97]
	s_mov_b32 m0, s20
	ds_read_b128 v[164:167], v195 offset:49152
	ds_read_b128 v[168:171], v195 offset:50176
	ds_read_b128 v[196:199], v195 offset:51200
	ds_read_b128 v[200:203], v195 offset:52224
	ds_read_b128 v[204:207], v195 offset:53248
	ds_read_b128 v[208:211], v195 offset:54272
	ds_read_b128 v[212:215], v195 offset:55296
	ds_read_b128 v[216:219], v195 offset:56320
	global_load_lds_dwordx4 v[82:83], off
	s_add_i32 m0, s20, 0x2000
	s_add_u32 s18, s18, 0x40080
	v_lshl_add_u64 v[82:83], v[246:247], 0, s[96:97]
	s_addc_u32 s19, s19, 0
	s_add_i32 s20, s23, s33
	global_load_lds_dwordx4 v[82:83], off
	v_lshl_add_u64 v[82:83], s[18:19], 0, v[176:177]
	s_mov_b32 m0, s20
	s_nop 0
	global_load_lds_dwordx4 v[82:83], off
	v_lshl_add_u64 v[82:83], s[18:19], 0, v[172:173]
	s_add_i32 m0, s20, 0x2000
	s_nop 0
	global_load_lds_dwordx4 v[82:83], off
	s_waitcnt vmcnt(6)
	s_waitcnt lgkmcnt(0)
	v_mfma_f32_16x16x32_bf16 v[60:63], v[132:135], v[164:167], v[60:63]
	v_mfma_f32_16x16x32_bf16 v[56:59], v[140:143], v[164:167], v[56:59]
	s_barrier
	s_setprio 1
	s_waitcnt lgkmcnt(0)
	v_mfma_f32_16x16x32_bf16 v[44:47], v[132:135], v[196:199], v[44:47]
	v_mfma_f32_16x16x32_bf16 v[40:43], v[140:143], v[196:199], v[40:43]
	v_mfma_f32_16x16x32_bf16 v[28:31], v[132:135], v[204:207], v[28:31]
	v_mfma_f32_16x16x32_bf16 v[24:27], v[140:143], v[204:207], v[24:27]
	v_mfma_f32_16x16x32_bf16 v[12:15], v[132:135], v[212:215], v[12:15]
	v_mfma_f32_16x16x32_bf16 v[8:11], v[140:143], v[212:215], v[8:11]
	v_mfma_f32_16x16x32_bf16 v[60:63], v[136:139], v[168:171], v[60:63]
	v_mfma_f32_16x16x32_bf16 v[56:59], v[144:147], v[168:171], v[56:59]
	v_mfma_f32_16x16x32_bf16 v[44:47], v[136:139], v[200:203], v[44:47]
	v_mfma_f32_16x16x32_bf16 v[40:43], v[144:147], v[200:203], v[40:43]
	v_mfma_f32_16x16x32_bf16 v[28:31], v[136:139], v[208:211], v[28:31]
	v_mfma_f32_16x16x32_bf16 v[24:27], v[144:147], v[208:211], v[24:27]
	v_mfma_f32_16x16x32_bf16 v[12:15], v[136:139], v[216:219], v[12:15]
	v_mfma_f32_16x16x32_bf16 v[8:11], v[144:147], v[216:219], v[8:11]
	v_mfma_f32_16x16x32_bf16 v[52:55], v[148:151], v[164:167], v[52:55]
	v_mfma_f32_16x16x32_bf16 v[48:51], v[156:159], v[164:167], v[48:51]
	v_mfma_f32_16x16x32_bf16 v[36:39], v[148:151], v[196:199], v[36:39]
	v_mfma_f32_16x16x32_bf16 v[32:35], v[156:159], v[196:199], v[32:35]
	v_mfma_f32_16x16x32_bf16 v[20:23], v[148:151], v[204:207], v[20:23]
	v_mfma_f32_16x16x32_bf16 v[16:19], v[156:159], v[204:207], v[16:19]
	v_mfma_f32_16x16x32_bf16 v[4:7], v[148:151], v[212:215], v[4:7]
	v_mfma_f32_16x16x32_bf16 v[0:3], v[156:159], v[212:215], v[0:3]
	v_mfma_f32_16x16x32_bf16 v[52:55], v[152:155], v[168:171], v[52:55]
	v_mfma_f32_16x16x32_bf16 v[48:51], v[160:163], v[168:171], v[48:51]
	v_mfma_f32_16x16x32_bf16 v[36:39], v[152:155], v[200:203], v[36:39]
	v_mfma_f32_16x16x32_bf16 v[32:35], v[160:163], v[200:203], v[32:35]
	v_mfma_f32_16x16x32_bf16 v[20:23], v[152:155], v[208:211], v[20:23]
	v_mfma_f32_16x16x32_bf16 v[16:19], v[160:163], v[208:211], v[16:19]
	v_mfma_f32_16x16x32_bf16 v[4:7], v[152:155], v[216:219], v[4:7]
	v_mfma_f32_16x16x32_bf16 v[0:3], v[160:163], v[216:219], v[0:3]
	s_setprio 0
	s_barrier
	s_add_i32 s18, s51, 2
	s_add_u32 s16, s16, 0x100
	s_addc_u32 s17, s17, 0
	s_cmp_gt_u32 s51, 13
	s_cbranch_scc1 .LBB0_154
	s_mov_b32 s51, s18
	s_cmp_lt_i32 s51, 12
	s_cbranch_scc1 .LBB0_148
	s_branch .LBB0_147

; #define PG8_STAGE(bufoff, gbase, voff) do { _Pragma("unroll") for (int _i = 0; _i < 2; ++_i) \
;         __builtin_amdgcn_global_load_lds((const unsigned*)((const char*)(gbase) + (voff)[_i]), (PG8_LAS unsigned*)(lds + (bufoff) + ldsw + _i * 8192), 16, 0, 0); } while (0)
; #define PG8_LDA(dst, b, h) do { _Pragma("unroll") for (int m = 0; m < 4; ++m) _Pragma("unroll") for (int k = 0; k < 2; ++k) dst[m][k] = *(const PG8_LAS bf16x8*)(lds + PG8_SA(b, h) + aoff + m * 2048 + k * 1024); } while (0)
; #define PG8_LDB(dst, b, h) do { _Pragma("unroll") for (int n = 0; n < 2; ++n) _Pragma("unroll") for (int k = 0; k < 2; ++k) dst[n][k] = *(const PG8_LAS bf16x8*)(lds + PG8_SB(b, h) + boff + n * 2048 + k * 1024); } while (0)
; #define PG8_MMA(ai, bj, At, Bt) do { __builtin_amdgcn_s_setprio(1); _Pragma("unroll") for (int m = 0; m < 4; ++m) _Pragma("unroll") for (int n = 0; n < 2; ++n) _Pragma("unroll") for (int k = 0; k < 2; ++k) \
;         acc[ai][bj][m][n] = __builtin_amdgcn_mfma_f32_16x16x32_bf16(Bt[n][k], At[m][k], acc[ai][bj][m][n], 0, 0, 0); __builtin_amdgcn_s_setprio(0); } while (0)
; #define PG8_WAIT_V(n) asm volatile("s_waitcnt vmcnt(" #n ")" ::: "memory")
; #define PG8_WAIT_L(n) asm volatile("s_waitcnt lgkmcnt(" #n ")" ::: "memory")
; #define PG8_BAR __builtin_amdgcn_s_barrier()
; #define PG8_SCHED __builtin_amdgcn_sched_barrier(0)
; template <class Epi, class Sched, bool ALIGN_EPI = false>
; __device__ __forceinline__ void gemm_phase(PG8_LAS unsigned char* lds, const Gemm g, const Sched& S, const Epi& E, int tid_in) {
;     ...
;             PG8_LDB(B0, 0, 0); PG8_LDB(B1, 0, 1); PG8_SCHED; PG8_LDA(At, 0, 0); PG8_STAGE(PG8_SA(1, 1), a1 + hstepA, voffA);
;             PG8_WAIT_V(8); PG8_WAIT_L(0); PG8_BAR; PG8_MMA(0, 0, At, B0); PG8_MMA(0, 1, At, B1); PG8_BAR; PG8_SCHED;
;             PG8_LDA(At, 0, 1); PG8_STAGE(PG8_SB(0, 0), b2, voffB); PG8_STAGE(PG8_SB(0, 1), b2 + hstepB, voffB); PG8_STAGE(PG8_SA(0, 0), a2, voffA);
;             PG8_WAIT_V(8); PG8_WAIT_L(0); PG8_BAR; PG8_MMA(1, 0, At, B0); PG8_MMA(1, 1, At, B1); PG8_BAR; PG8_SCHED;
.LBB0_267:
	s_add_i32 s63, s58, 2
	s_add_u32 s22, s60, 0x80
	s_addc_u32 s23, s61, 0
	s_add_i32 s89, 0, 0x10000
	s_cmp_eq_u32 s77, s58
	s_cselect_b32 s59, s19, s23
	s_cselect_b32 s58, s18, s22
	v_add_u32_e32 v80, s89, v245
	s_cselect_b32 s23, s35, s62
	s_cselect_b32 s22, s34, s57
	s_add_i32 s90, 0, 0x14000
	ds_read_b128 v[130:133], v80
	ds_read_b128 v[134:137], v80 offset:1024
	ds_read_b128 v[138:141], v80 offset:2048
	ds_read_b128 v[142:145], v80 offset:3072
	v_add_u32_e32 v80, s90, v245
	ds_read_b128 v[146:149], v80
	ds_read_b128 v[150:153], v80 offset:1024
	ds_read_b128 v[154:157], v80 offset:2048
	ds_read_b128 v[158:161], v80 offset:3072
	v_lshl_add_u64 v[210:211], s[60:61], 0, v[194:195]
	s_add_i32 m0, s70, 0xc000
	ds_read_b128 v[162:165], v248
	ds_read_b128 v[166:169], v248 offset:1024
	ds_read_b128 v[170:173], v248 offset:2048
	ds_read_b128 v[174:177], v248 offset:3072
	ds_read_b128 v[178:181], v248 offset:4096
	ds_read_b128 v[198:201], v248 offset:5120
	ds_read_b128 v[202:205], v248 offset:6144
	ds_read_b128 v[206:209], v248 offset:7168
	v_lshl_add_u64 v[212:213], s[60:61], 0, v[184:185]
	s_mov_b32 m0, s74
	v_lshl_add_u64 v[214:215], s[60:61], 0, v[188:189]
	global_load_lds_dwordx4 v[212:213], off
	s_mov_b32 m0, s75
	s_nop 0
	global_load_lds_dwordx4 v[214:215], off
	s_add_i32 m0, s70, 0xc000
	s_nop 0
	global_load_lds_dwordx4 v[210:211], off
	v_lshl_add_u64 v[210:211], s[60:61], 0, v[196:197]
	s_add_i32 m0, s70, 0xe000
	s_nop 0
	global_load_lds_dwordx4 v[210:211], off
	s_waitcnt vmcnt(8)
	s_waitcnt lgkmcnt(0)
	v_mfma_f32_16x16x32_bf16 v[4:7], v[130:133], v[162:165], v[4:7]
	v_mfma_f32_16x16x32_bf16 v[0:3], v[138:141], v[162:165], v[0:3]
	s_barrier
	s_setprio 1
	s_waitcnt lgkmcnt(0)
	v_mfma_f32_16x16x32_bf16 v[20:23], v[130:133], v[170:173], v[20:23]
	v_mfma_f32_16x16x32_bf16 v[16:19], v[138:141], v[170:173], v[16:19]
	v_mfma_f32_16x16x32_bf16 v[36:39], v[130:133], v[178:181], v[36:39]
	v_mfma_f32_16x16x32_bf16 v[32:35], v[138:141], v[178:181], v[32:35]
	v_mfma_f32_16x16x32_bf16 v[52:55], v[130:133], v[202:205], v[52:55]
	v_mfma_f32_16x16x32_bf16 v[48:51], v[138:141], v[202:205], v[48:51]
	v_mfma_f32_16x16x32_bf16 v[4:7], v[134:137], v[166:169], v[4:7]
	v_mfma_f32_16x16x32_bf16 v[0:3], v[142:145], v[166:169], v[0:3]
	v_mfma_f32_16x16x32_bf16 v[20:23], v[134:137], v[174:177], v[20:23]
	v_mfma_f32_16x16x32_bf16 v[16:19], v[142:145], v[174:177], v[16:19]
	v_mfma_f32_16x16x32_bf16 v[36:39], v[134:137], v[198:201], v[36:39]
	v_mfma_f32_16x16x32_bf16 v[32:35], v[142:145], v[198:201], v[32:35]
	v_mfma_f32_16x16x32_bf16 v[52:55], v[134:137], v[206:209], v[52:55]
	v_mfma_f32_16x16x32_bf16 v[48:51], v[142:145], v[206:209], v[48:51]
	v_mfma_f32_16x16x32_bf16 v[12:15], v[146:149], v[162:165], v[12:15]
	v_mfma_f32_16x16x32_bf16 v[8:11], v[154:157], v[162:165], v[8:11]
	v_mfma_f32_16x16x32_bf16 v[28:31], v[146:149], v[170:173], v[28:31]
	v_mfma_f32_16x16x32_bf16 v[24:27], v[154:157], v[170:173], v[24:27]
	v_mfma_f32_16x16x32_bf16 v[44:47], v[146:149], v[178:181], v[44:47]
	v_mfma_f32_16x16x32_bf16 v[40:43], v[154:157], v[178:181], v[40:43]
	v_mfma_f32_16x16x32_bf16 v[60:63], v[146:149], v[202:205], v[60:63]
	v_mfma_f32_16x16x32_bf16 v[56:59], v[154:157], v[202:205], v[56:59]
	v_mfma_f32_16x16x32_bf16 v[12:15], v[150:153], v[166:169], v[12:15]
	v_mfma_f32_16x16x32_bf16 v[8:11], v[158:161], v[166:169], v[8:11]
	v_mfma_f32_16x16x32_bf16 v[28:31], v[150:153], v[174:177], v[28:31]
	v_mfma_f32_16x16x32_bf16 v[24:27], v[158:161], v[174:177], v[24:27]
	v_mfma_f32_16x16x32_bf16 v[44:47], v[150:153], v[198:201], v[44:47]
	v_mfma_f32_16x16x32_bf16 v[40:43], v[158:161], v[198:201], v[40:43]
	v_mfma_f32_16x16x32_bf16 v[60:63], v[150:153], v[206:209], v[60:63]
	v_mfma_f32_16x16x32_bf16 v[56:59], v[158:161], v[206:209], v[56:59]
	s_setprio 0
	s_barrier
	s_add_i32 s89, s89, s69
	v_lshl_add_u64 v[210:211], s[22:23], 0, v[186:187]
	s_mov_b32 m0, s89
	ds_read_b128 v[162:165], v248 offset:16384
	ds_read_b128 v[166:169], v248 offset:17408
	ds_read_b128 v[170:173], v248 offset:18432
	ds_read_b128 v[174:177], v248 offset:19456
	ds_read_b128 v[178:181], v248 offset:20480
	ds_read_b128 v[198:201], v248 offset:21504
	ds_read_b128 v[202:205], v248 offset:22528
	ds_read_b128 v[206:209], v248 offset:23552
	global_load_lds_dwordx4 v[210:211], off
	s_add_i32 m0, s89, 0x2000
	v_lshl_add_u64 v[212:213], s[22:23], 0, v[190:191]
	s_add_u32 s22, s22, s33
	s_addc_u32 s23, s23, 0
	s_add_i32 s89, s90, s69
	global_load_lds_dwordx4 v[212:213], off
	v_lshl_add_u64 v[214:215], s[22:23], 0, v[186:187]
	s_mov_b32 m0, s89
	v_lshl_add_u64 v[216:217], s[22:23], 0, v[190:191]
	global_load_lds_dwordx4 v[214:215], off
	s_add_i32 m0, s89, 0x2000
	v_lshl_add_u64 v[218:219], s[58:59], 0, v[184:185]
	global_load_lds_dwordx4 v[216:217], off
	v_lshl_add_u64 v[228:229], s[58:59], 0, v[188:189]
	s_waitcnt vmcnt(6)
	s_waitcnt lgkmcnt(0)
	v_mfma_f32_16x16x32_bf16 v[64:67], v[130:133], v[162:165], v[64:67]
	v_mfma_f32_16x16x32_bf16 v[68:71], v[138:141], v[162:165], v[68:71]
	s_barrier
; #define PG8_STAGE(bufoff, gbase, voff) do { _Pragma("unroll") for (int _i = 0; _i < 2; ++_i) \
;         __builtin_amdgcn_global_load_lds((const unsigned*)((const char*)(gbase) + (voff)[_i]), (PG8_LAS unsigned*)(lds + (bufoff) + ldsw + _i * 8192), 16, 0, 0); } while (0)
; #define PG8_LDA(dst, b, h) do { _Pragma("unroll") for (int m = 0; m < 4; ++m) _Pragma("unroll") for (int k = 0; k < 2; ++k) dst[m][k] = *(const PG8_LAS bf16x8*)(lds + PG8_SA(b, h) + aoff + m * 2048 + k * 1024); } while (0)
; #define PG8_LDB(dst, b, h) do { _Pragma("unroll") for (int n = 0; n < 2; ++n) _Pragma("unroll") for (int k = 0; k < 2; ++k) dst[n][k] = *(const PG8_LAS bf16x8*)(lds + PG8_SB(b, h) + boff + n * 2048 + k * 1024); } while (0)
; #define PG8_MMA(ai, bj, At, Bt) do { __builtin_amdgcn_s_setprio(1); _Pragma("unroll") for (int m = 0; m < 4; ++m) _Pragma("unroll") for (int n = 0; n < 2; ++n) _Pragma("unroll") for (int k = 0; k < 2; ++k) \
;         acc[ai][bj][m][n] = __builtin_amdgcn_mfma_f32_16x16x32_bf16(Bt[n][k], At[m][k], acc[ai][bj][m][n], 0, 0, 0); __builtin_amdgcn_s_setprio(0); } while (0)
; #define PG8_WAIT_V(n) asm volatile("s_waitcnt vmcnt(" #n ")" ::: "memory")
; #define PG8_WAIT_L(n) asm volatile("s_waitcnt lgkmcnt(" #n ")" ::: "memory")
; #define PG8_BAR __builtin_amdgcn_s_barrier()
; #define PG8_SCHED __builtin_amdgcn_sched_barrier(0)
; template <class Epi, class Sched, bool ALIGN_EPI = false>
; __device__ __forceinline__ void gemm_phase(PG8_LAS unsigned char* lds, const Gemm g, const Sched& S, const Epi& E, int tid_in) {
;     ...
;             PG8_WAIT_V(8); PG8_WAIT_L(0); PG8_BAR; PG8_MMA(1, 0, At, B0); PG8_MMA(1, 1, At, B1); PG8_BAR; PG8_SCHED;
;             PG8_LDB(B0, 1, 0); PG8_LDB(B1, 1, 1); PG8_SCHED; PG8_LDA(At, 1, 0); PG8_STAGE(PG8_SA(0, 1), a2 + hstepA, voffA);
;             PG8_WAIT_V(8); PG8_WAIT_L(0); PG8_BAR; PG8_MMA(0, 0, At, B0); PG8_MMA(0, 1, At, B1); PG8_BAR; PG8_SCHED;
	s_setprio 1
	s_waitcnt lgkmcnt(0)
	v_mfma_f32_16x16x32_bf16 v[82:85], v[130:133], v[170:173], v[82:85]
	v_mfma_f32_16x16x32_bf16 v[86:89], v[138:141], v[170:173], v[86:89]
	v_mfma_f32_16x16x32_bf16 v[98:101], v[130:133], v[178:181], v[98:101]
	v_mfma_f32_16x16x32_bf16 v[102:105], v[138:141], v[178:181], v[102:105]
	v_mfma_f32_16x16x32_bf16 v[114:117], v[130:133], v[202:205], v[114:117]
	v_mfma_f32_16x16x32_bf16 v[118:121], v[138:141], v[202:205], v[118:121]
	v_mfma_f32_16x16x32_bf16 v[64:67], v[134:137], v[166:169], v[64:67]
	v_mfma_f32_16x16x32_bf16 v[68:71], v[142:145], v[166:169], v[68:71]
	v_mfma_f32_16x16x32_bf16 v[82:85], v[134:137], v[174:177], v[82:85]
	v_mfma_f32_16x16x32_bf16 v[86:89], v[142:145], v[174:177], v[86:89]
	v_mfma_f32_16x16x32_bf16 v[98:101], v[134:137], v[198:201], v[98:101]
	v_mfma_f32_16x16x32_bf16 v[102:105], v[142:145], v[198:201], v[102:105]
	v_mfma_f32_16x16x32_bf16 v[114:117], v[134:137], v[206:209], v[114:117]
	v_mfma_f32_16x16x32_bf16 v[118:121], v[142:145], v[206:209], v[118:121]
	v_mfma_f32_16x16x32_bf16 v[76:79], v[146:149], v[162:165], v[76:79]
	v_mfma_f32_16x16x32_bf16 v[72:75], v[154:157], v[162:165], v[72:75]
	v_mfma_f32_16x16x32_bf16 v[94:97], v[146:149], v[170:173], v[94:97]
	v_mfma_f32_16x16x32_bf16 v[90:93], v[154:157], v[170:173], v[90:93]
	v_mfma_f32_16x16x32_bf16 v[110:113], v[146:149], v[178:181], v[110:113]
	v_mfma_f32_16x16x32_bf16 v[106:109], v[154:157], v[178:181], v[106:109]
	v_mfma_f32_16x16x32_bf16 v[126:129], v[146:149], v[202:205], v[126:129]
	v_mfma_f32_16x16x32_bf16 v[122:125], v[154:157], v[202:205], v[122:125]
	v_mfma_f32_16x16x32_bf16 v[76:79], v[150:153], v[166:169], v[76:79]
	v_mfma_f32_16x16x32_bf16 v[72:75], v[158:161], v[166:169], v[72:75]
	v_mfma_f32_16x16x32_bf16 v[94:97], v[150:153], v[174:177], v[94:97]
	v_mfma_f32_16x16x32_bf16 v[90:93], v[158:161], v[174:177], v[90:93]
	v_mfma_f32_16x16x32_bf16 v[110:113], v[150:153], v[198:201], v[110:113]
	v_mfma_f32_16x16x32_bf16 v[106:109], v[158:161], v[198:201], v[106:109]
	v_mfma_f32_16x16x32_bf16 v[126:129], v[150:153], v[206:209], v[126:129]
	v_mfma_f32_16x16x32_bf16 v[122:125], v[158:161], v[206:209], v[122:125]
	s_setprio 0
	s_barrier
	s_add_i32 s89, 0, 0x18000
	v_add_u32_e32 v80, s89, v245
	s_add_i32 s90, 0, 0x1c000
	ds_read_b128 v[130:133], v80
	ds_read_b128 v[134:137], v80 offset:1024
	ds_read_b128 v[138:141], v80 offset:2048
	ds_read_b128 v[142:145], v80 offset:3072
	v_add_u32_e32 v80, s90, v245
	ds_read_b128 v[146:149], v80
	ds_read_b128 v[150:153], v80 offset:1024
	ds_read_b128 v[154:157], v80 offset:2048
	ds_read_b128 v[158:161], v80 offset:3072
	s_add_u32 s22, s58, s0
	s_addc_u32 s23, s59, 0
	s_mov_b32 m0, s70
	v_lshl_add_u64 v[222:223], s[22:23], 0, v[184:185]
	ds_read_b128 v[162:165], v248 offset:32768
	ds_read_b128 v[166:169], v248 offset:33792
	ds_read_b128 v[170:173], v248 offset:34816
	ds_read_b128 v[174:177], v248 offset:35840
	ds_read_b128 v[178:181], v248 offset:36864
	ds_read_b128 v[198:201], v248 offset:37888
	ds_read_b128 v[202:205], v248 offset:38912
	ds_read_b128 v[206:209], v248 offset:39936
	global_load_lds_dwordx4 v[218:219], off
	s_mov_b32 m0, s71
	s_nop 0
	global_load_lds_dwordx4 v[228:229], off
	s_mov_b32 m0, s72
	s_nop 0
	global_load_lds_dwordx4 v[222:223], off
	v_lshl_add_u64 v[222:223], s[22:23], 0, v[188:189]
	s_mov_b32 m0, s73
	s_nop 0
	global_load_lds_dwordx4 v[222:223], off
	s_waitcnt vmcnt(8)
	s_waitcnt lgkmcnt(0)
	v_mfma_f32_16x16x32_bf16 v[4:7], v[130:133], v[162:165], v[4:7]
	v_mfma_f32_16x16x32_bf16 v[0:3], v[138:141], v[162:165], v[0:3]
	s_barrier
; #define PG8_STAGE(bufoff, gbase, voff) do { _Pragma("unroll") for (int _i = 0; _i < 2; ++_i) \
;         __builtin_amdgcn_global_load_lds((const unsigned*)((const char*)(gbase) + (voff)[_i]), (PG8_LAS unsigned*)(lds + (bufoff) + ldsw + _i * 8192), 16, 0, 0); } while (0)
; #define PG8_LDA(dst, b, h) do { _Pragma("unroll") for (int m = 0; m < 4; ++m) _Pragma("unroll") for (int k = 0; k < 2; ++k) dst[m][k] = *(const PG8_LAS bf16x8*)(lds + PG8_SA(b, h) + aoff + m * 2048 + k * 1024); } while (0)
; #define PG8_MMA(ai, bj, At, Bt) do { __builtin_amdgcn_s_setprio(1); _Pragma("unroll") for (int m = 0; m < 4; ++m) _Pragma("unroll") for (int n = 0; n < 2; ++n) _Pragma("unroll") for (int k = 0; k < 2; ++k) \
;         acc[ai][bj][m][n] = __builtin_amdgcn_mfma_f32_16x16x32_bf16(Bt[n][k], At[m][k], acc[ai][bj][m][n], 0, 0, 0); __builtin_amdgcn_s_setprio(0); } while (0)
; #define PG8_WAIT_V(n) asm volatile("s_waitcnt vmcnt(" #n ")" ::: "memory")
; #define PG8_WAIT_L(n) asm volatile("s_waitcnt lgkmcnt(" #n ")" ::: "memory")
; #define PG8_BAR __builtin_amdgcn_s_barrier()
; #define PG8_SCHED __builtin_amdgcn_sched_barrier(0)
; template <class Epi, class Sched, bool ALIGN_EPI = false>
; __device__ __forceinline__ void gemm_phase(PG8_LAS unsigned char* lds, const Gemm g, const Sched& S, const Epi& E, int tid_in) {
;     ...
;             PG8_WAIT_V(8); PG8_WAIT_L(0); PG8_BAR; PG8_MMA(0, 0, At, B0); PG8_MMA(0, 1, At, B1); PG8_BAR; PG8_SCHED;
;             PG8_LDA(At, 1, 1); PG8_STAGE(PG8_SB(1, 0), b3, voffB); PG8_STAGE(PG8_SB(1, 1), b3 + hstepB, voffB); PG8_STAGE(PG8_SA(1, 0), a3, voffA);
;             PG8_WAIT_V(8); PG8_WAIT_L(0); PG8_BAR; PG8_MMA(1, 0, At, B0); PG8_MMA(1, 1, At, B1); PG8_BAR; PG8_SCHED;
;         }
	s_setprio 1
	s_waitcnt lgkmcnt(0)
	v_mfma_f32_16x16x32_bf16 v[20:23], v[130:133], v[170:173], v[20:23]
	v_mfma_f32_16x16x32_bf16 v[16:19], v[138:141], v[170:173], v[16:19]
	v_mfma_f32_16x16x32_bf16 v[36:39], v[130:133], v[178:181], v[36:39]
	v_mfma_f32_16x16x32_bf16 v[32:35], v[138:141], v[178:181], v[32:35]
	v_mfma_f32_16x16x32_bf16 v[52:55], v[130:133], v[202:205], v[52:55]
	v_mfma_f32_16x16x32_bf16 v[48:51], v[138:141], v[202:205], v[48:51]
	v_mfma_f32_16x16x32_bf16 v[4:7], v[134:137], v[166:169], v[4:7]
	v_mfma_f32_16x16x32_bf16 v[0:3], v[142:145], v[166:169], v[0:3]
	v_mfma_f32_16x16x32_bf16 v[20:23], v[134:137], v[174:177], v[20:23]
	v_mfma_f32_16x16x32_bf16 v[16:19], v[142:145], v[174:177], v[16:19]
	v_mfma_f32_16x16x32_bf16 v[36:39], v[134:137], v[198:201], v[36:39]
	v_mfma_f32_16x16x32_bf16 v[32:35], v[142:145], v[198:201], v[32:35]
	v_mfma_f32_16x16x32_bf16 v[52:55], v[134:137], v[206:209], v[52:55]
	v_mfma_f32_16x16x32_bf16 v[48:51], v[142:145], v[206:209], v[48:51]
	v_mfma_f32_16x16x32_bf16 v[12:15], v[146:149], v[162:165], v[12:15]
	v_mfma_f32_16x16x32_bf16 v[8:11], v[154:157], v[162:165], v[8:11]
	v_mfma_f32_16x16x32_bf16 v[28:31], v[146:149], v[170:173], v[28:31]
	v_mfma_f32_16x16x32_bf16 v[24:27], v[154:157], v[170:173], v[24:27]
	v_mfma_f32_16x16x32_bf16 v[44:47], v[146:149], v[178:181], v[44:47]
	v_mfma_f32_16x16x32_bf16 v[40:43], v[154:157], v[178:181], v[40:43]
	v_mfma_f32_16x16x32_bf16 v[60:63], v[146:149], v[202:205], v[60:63]
	v_mfma_f32_16x16x32_bf16 v[56:59], v[154:157], v[202:205], v[56:59]
	v_mfma_f32_16x16x32_bf16 v[12:15], v[150:153], v[166:169], v[12:15]
	v_mfma_f32_16x16x32_bf16 v[8:11], v[158:161], v[166:169], v[8:11]
	v_mfma_f32_16x16x32_bf16 v[28:31], v[150:153], v[174:177], v[28:31]
	v_mfma_f32_16x16x32_bf16 v[24:27], v[158:161], v[174:177], v[24:27]
	v_mfma_f32_16x16x32_bf16 v[44:47], v[150:153], v[198:201], v[44:47]
	v_mfma_f32_16x16x32_bf16 v[40:43], v[158:161], v[198:201], v[40:43]
	v_mfma_f32_16x16x32_bf16 v[60:63], v[150:153], v[206:209], v[60:63]
	v_mfma_f32_16x16x32_bf16 v[56:59], v[158:161], v[206:209], v[56:59]
	s_setprio 0
	s_barrier
	s_add_i32 s22, s89, s69
	v_lshl_add_u64 v[210:211], v[210:211], 0, s[96:97]
	s_mov_b32 m0, s22
	ds_read_b128 v[162:165], v248 offset:49152
	ds_read_b128 v[166:169], v248 offset:50176
	ds_read_b128 v[170:173], v248 offset:51200
	ds_read_b128 v[174:177], v248 offset:52224
	ds_read_b128 v[178:181], v248 offset:53248
	ds_read_b128 v[198:201], v248 offset:54272
	ds_read_b128 v[202:205], v248 offset:55296
	ds_read_b128 v[206:209], v248 offset:56320
	global_load_lds_dwordx4 v[210:211], off
	v_lshl_add_u64 v[210:211], v[212:213], 0, s[96:97]
	s_add_i32 m0, s22, 0x2000
	s_add_i32 s22, s90, s69
	global_load_lds_dwordx4 v[210:211], off
	v_lshl_add_u64 v[210:211], v[214:215], 0, s[96:97]
	s_mov_b32 m0, s22
	s_nop 0
	global_load_lds_dwordx4 v[210:211], off
	v_lshl_add_u64 v[210:211], v[216:217], 0, s[96:97]
	s_add_i32 m0, s22, 0x2000
	s_nop 0
	global_load_lds_dwordx4 v[210:211], off
	s_waitcnt vmcnt(6)
	s_waitcnt lgkmcnt(0)
	v_mfma_f32_16x16x32_bf16 v[64:67], v[130:133], v[162:165], v[64:67]
	v_mfma_f32_16x16x32_bf16 v[68:71], v[138:141], v[162:165], v[68:71]
	s_barrier
	s_setprio 1
	s_waitcnt lgkmcnt(0)
	v_mfma_f32_16x16x32_bf16 v[82:85], v[130:133], v[170:173], v[82:85]
	v_mfma_f32_16x16x32_bf16 v[86:89], v[138:141], v[170:173], v[86:89]
	v_mfma_f32_16x16x32_bf16 v[98:101], v[130:133], v[178:181], v[98:101]
	v_mfma_f32_16x16x32_bf16 v[102:105], v[138:141], v[178:181], v[102:105]
	v_mfma_f32_16x16x32_bf16 v[114:117], v[130:133], v[202:205], v[114:117]
	v_mfma_f32_16x16x32_bf16 v[118:121], v[138:141], v[202:205], v[118:121]
	v_mfma_f32_16x16x32_bf16 v[64:67], v[134:137], v[166:169], v[64:67]
	v_mfma_f32_16x16x32_bf16 v[68:71], v[142:145], v[166:169], v[68:71]
	v_mfma_f32_16x16x32_bf16 v[82:85], v[134:137], v[174:177], v[82:85]
	v_mfma_f32_16x16x32_bf16 v[86:89], v[142:145], v[174:177], v[86:89]
	v_mfma_f32_16x16x32_bf16 v[98:101], v[134:137], v[198:201], v[98:101]
	v_mfma_f32_16x16x32_bf16 v[102:105], v[142:145], v[198:201], v[102:105]
	v_mfma_f32_16x16x32_bf16 v[114:117], v[134:137], v[206:209], v[114:117]
	v_mfma_f32_16x16x32_bf16 v[118:121], v[142:145], v[206:209], v[118:121]
	v_mfma_f32_16x16x32_bf16 v[76:79], v[146:149], v[162:165], v[76:79]
	v_mfma_f32_16x16x32_bf16 v[72:75], v[154:157], v[162:165], v[72:75]
	v_mfma_f32_16x16x32_bf16 v[94:97], v[146:149], v[170:173], v[94:97]
	v_mfma_f32_16x16x32_bf16 v[90:93], v[154:157], v[170:173], v[90:93]
	v_mfma_f32_16x16x32_bf16 v[110:113], v[146:149], v[178:181], v[110:113]
	v_mfma_f32_16x16x32_bf16 v[106:109], v[154:157], v[178:181], v[106:109]
	v_mfma_f32_16x16x32_bf16 v[126:129], v[146:149], v[202:205], v[126:129]
	v_mfma_f32_16x16x32_bf16 v[122:125], v[154:157], v[202:205], v[122:125]
	v_mfma_f32_16x16x32_bf16 v[76:79], v[150:153], v[166:169], v[76:79]
	v_mfma_f32_16x16x32_bf16 v[72:75], v[158:161], v[166:169], v[72:75]
	v_mfma_f32_16x16x32_bf16 v[94:97], v[150:153], v[174:177], v[94:97]
	v_mfma_f32_16x16x32_bf16 v[90:93], v[158:161], v[174:177], v[90:93]
	v_mfma_f32_16x16x32_bf16 v[110:113], v[150:153], v[198:201], v[110:113]
	v_mfma_f32_16x16x32_bf16 v[106:109], v[158:161], v[198:201], v[106:109]
	v_mfma_f32_16x16x32_bf16 v[126:129], v[150:153], v[206:209], v[126:129]
	v_mfma_f32_16x16x32_bf16 v[122:125], v[158:161], v[206:209], v[122:125]
	s_setprio 0
	s_barrier
	s_add_u32 s60, s60, 0x100
	s_addc_u32 s61, s61, 0
	s_add_u32 s57, s57, 0x100
	s_addc_u32 s62, s62, 0
	s_cmp_ge_u32 s63, s76
	s_mov_b32 s58, s63
	s_cbranch_scc0 .LBB0_267
	s_and_b64 vcc, exec, s[14:15]
	s_cbranch_vccnz .LBB0_271
	s_cmp_lt_i32 s64, 3
	s_mov_b64 s[58:59], -1
	s_cbranch_scc0 .LBB0_272

; __device__ __forceinline__ unsigned cvt_pk_bf16(float lo, float hi) { unsigned r; asm volatile("v_cvt_pk_bf16_f32 %0, %1, %2" : "=v"(r) : "v"(lo), "v"(hi)); return r; }
; #define PG8_ST(v, p) __builtin_nontemporal_store((v), (p))
;     __device__ __forceinline__ float* out() const { return *(const __attribute__((address_space(4))) fptr_t*)(p + 256); }
; __device__ __forceinline__ void epi_res(float* out, const f32x4 (&acc)[2][2][4][2], const Unit& u, int wr, int wc, int fr, int fq) {
;         const int row0 = u.pm * BM + wr * 64 + fr, col0 = u.pn * BM + wc * 32 + 8 * fq;
;         bf16_t* hb = (bf16_t*)out;
; #pragma unroll
;         for (int ai = 0; ai < 2; ++ai)
; #pragma unroll
;             for (int m = 0; m < 4; ++m) { const size_t off = (size_t)(row0 + ai * HALF + m * 16) * 1024 + col0;
; #pragma unroll
;                 for (int bj = 0; bj < 2; ++bj) { const f32x4 o0 = acc[ai][bj][m][0], o1 = acc[ai][bj][m][1];
;                     u32x4 w; w.x = cvt_pk_bf16(o0[0], o0[1]); w.y = cvt_pk_bf16(o0[2], o0[3]); w.z = cvt_pk_bf16(o1[0], o1[1]); w.w = cvt_pk_bf16(o1[2], o1[3]); PG8_ST(w, (u32x4*)(hb + off + bj * HALF)); } }
; }
; __device__ __forceinline__ void epi_res_norm(float* out, bf16_t* xn, const float* gain, float* slots, unsigned* cnt, bool fin, const f32x4 (&acc)[2][2][4][2], const Unit& u, int wr, int wc, int fr, int fq) {
;     ...
;         if (fq == 0) {
; #pragma unroll
;             for (int g = 0; g < 8; ++g) __hip_atomic_store(slots + (size_t)(row0 + (g >> 2) * HALF + (g & 3) * 16) * 16 + u.pn * 4 + wc, sqv[g], __ATOMIC_RELAXED, __HIP_MEMORY_SCOPE_AGENT); }
;         asm volatile("s_waitcnt vmcnt(0)" ::: "memory");
;         if (fr == 0 && fq == 0) __hip_atomic_fetch_add(cnt + 64 * u.pm, 1u, __ATOMIC_RELAXED, __HIP_MEMORY_SCOPE_AGENT);
;         if (!fin) epi_res(out, acc, u, wr, wc, fr, fq);
.LBB0_282:
	s_or_b64 exec, exec, s[58:59]
	v_lshl_or_b32 v200, s87, 8, v247
	v_ashrrev_i32_e32 v201, 31, v200
	s_andn2_b64 vcc, exec, s[30:31]
	s_cbranch_vccnz .Lhs2_skip
	v_lshl_add_u64 v[136:137], v[200:201], 1, s[6:7]
	v_lshlrev_b64 v[130:131], 11, v[174:175]
	v_lshl_add_u64 v[130:131], v[136:137], 0, v[130:131]
	v_cvt_pk_bf16_f32 v132, v4, v5
	v_cvt_pk_bf16_f32 v133, v6, v7
	v_cvt_pk_bf16_f32 v134, v0, v1
	v_cvt_pk_bf16_f32 v135, v2, v3
	global_store_dwordx4 v[130:131], v[132:135], off
	s_mov_b64 s[22:23], 0x40000
	s_nop 0
	v_cvt_pk_bf16_f32 v132, v12, v13
	v_cvt_pk_bf16_f32 v133, v14, v15
	v_cvt_pk_bf16_f32 v134, v8, v9
	v_cvt_pk_bf16_f32 v135, v10, v11
	global_store_dwordx4 v[130:131], v[132:135], off offset:256
	s_nop 1
	v_lshlrev_b64 v[132:133], 11, v[210:211]
	v_lshl_add_u64 v[138:139], v[136:137], 0, v[132:133]
	v_cvt_pk_bf16_f32 v132, v20, v21
	v_cvt_pk_bf16_f32 v133, v22, v23
	v_cvt_pk_bf16_f32 v134, v16, v17
	v_cvt_pk_bf16_f32 v135, v18, v19
	global_store_dwordx4 v[138:139], v[132:135], off
	s_nop 1
	v_cvt_pk_bf16_f32 v132, v28, v29
	v_cvt_pk_bf16_f32 v133, v30, v31
	v_cvt_pk_bf16_f32 v134, v24, v25
	v_cvt_pk_bf16_f32 v135, v26, v27
	global_store_dwordx4 v[138:139], v[132:135], off offset:256
	s_nop 1
	v_lshlrev_b64 v[132:133], 11, v[208:209]
	v_lshl_add_u64 v[138:139], v[136:137], 0, v[132:133]
	v_cvt_pk_bf16_f32 v132, v36, v37
	v_cvt_pk_bf16_f32 v133, v38, v39
	v_cvt_pk_bf16_f32 v134, v32, v33
	v_cvt_pk_bf16_f32 v135, v34, v35
	global_store_dwordx4 v[138:139], v[132:135], off
	s_nop 1
	v_cvt_pk_bf16_f32 v132, v44, v45
	v_cvt_pk_bf16_f32 v133, v46, v47
	v_cvt_pk_bf16_f32 v134, v40, v41
	v_cvt_pk_bf16_f32 v135, v42, v43
	global_store_dwordx4 v[138:139], v[132:135], off offset:256
	s_nop 1
	v_lshlrev_b64 v[132:133], 11, v[206:207]
	v_lshl_add_u64 v[136:137], v[136:137], 0, v[132:133]
	v_cvt_pk_bf16_f32 v132, v52, v53
	v_cvt_pk_bf16_f32 v133, v54, v55
	v_cvt_pk_bf16_f32 v134, v48, v49
	v_cvt_pk_bf16_f32 v135, v50, v51
	global_store_dwordx4 v[136:137], v[132:135], off
	s_nop 1
	v_cvt_pk_bf16_f32 v132, v60, v61
	v_cvt_pk_bf16_f32 v133, v62, v63
	v_cvt_pk_bf16_f32 v134, v56, v57
	v_cvt_pk_bf16_f32 v135, v58, v59
	global_store_dwordx4 v[136:137], v[132:135], off offset:256
	v_lshl_add_u64 v[136:137], v[130:131], 0, s[22:23]
	s_mov_b32 s22, 0x40000
	v_add_co_u32_e32 v138, vcc, s22, v130
	v_cvt_pk_bf16_f32 v132, v64, v65
	v_cvt_pk_bf16_f32 v133, v66, v67
	v_cvt_pk_bf16_f32 v134, v68, v69
	v_cvt_pk_bf16_f32 v135, v70, v71
	s_nop 1
	v_addc_co_u32_e32 v139, vcc, 0, v131, vcc
	s_mov_b64 s[22:23], 0x48000
	global_store_dwordx4 v[138:139], v[132:135], off
	s_nop 1
	v_cvt_pk_bf16_f32 v132, v76, v77
	v_cvt_pk_bf16_f32 v133, v78, v79
	v_cvt_pk_bf16_f32 v134, v72, v73
	v_cvt_pk_bf16_f32 v135, v74, v75
	global_store_dwordx4 v[136:137], v[132:135], off offset:256
	v_lshl_add_u64 v[136:137], v[130:131], 0, s[22:23]
	s_mov_b32 s22, 0x48000
	v_add_co_u32_e32 v138, vcc, s22, v130
	v_cvt_pk_bf16_f32 v132, v82, v83
	v_cvt_pk_bf16_f32 v133, v84, v85
	v_cvt_pk_bf16_f32 v134, v86, v87
	v_cvt_pk_bf16_f32 v135, v88, v89
	s_nop 1
	v_addc_co_u32_e32 v139, vcc, 0, v131, vcc
	s_mov_b64 s[22:23], 0x50000
	global_store_dwordx4 v[138:139], v[132:135], off
	s_nop 1
	v_cvt_pk_bf16_f32 v132, v94, v95
	v_cvt_pk_bf16_f32 v133, v96, v97
	v_cvt_pk_bf16_f32 v134, v90, v91
	v_cvt_pk_bf16_f32 v135, v92, v93
	global_store_dwordx4 v[136:137], v[132:135], off offset:256
	v_lshl_add_u64 v[136:137], v[130:131], 0, s[22:23]
	s_mov_b32 s22, 0x50000
	v_add_co_u32_e32 v138, vcc, s22, v130
	v_cvt_pk_bf16_f32 v132, v98, v99
	v_cvt_pk_bf16_f32 v133, v100, v101
	v_cvt_pk_bf16_f32 v134, v102, v103
	v_cvt_pk_bf16_f32 v135, v104, v105
	s_nop 1
	v_addc_co_u32_e32 v139, vcc, 0, v131, vcc
	s_mov_b64 s[22:23], 0x58000
	global_store_dwordx4 v[138:139], v[132:135], off
	s_nop 1
	v_cvt_pk_bf16_f32 v132, v110, v111
	v_cvt_pk_bf16_f32 v133, v112, v113
	v_cvt_pk_bf16_f32 v134, v106, v107
	v_cvt_pk_bf16_f32 v135, v108, v109
	global_store_dwordx4 v[136:137], v[132:135], off offset:256
	v_lshl_add_u64 v[136:137], v[130:131], 0, s[22:23]
	s_mov_b32 s22, 0x58000
	v_add_co_u32_e32 v130, vcc, s22, v130
	v_cvt_pk_bf16_f32 v132, v114, v115
	v_cvt_pk_bf16_f32 v133, v116, v117
	v_cvt_pk_bf16_f32 v134, v118, v119
	v_cvt_pk_bf16_f32 v135, v120, v121
	s_nop 1
	v_addc_co_u32_e32 v131, vcc, 0, v131, vcc
	global_store_dwordx4 v[130:131], v[132:135], off
	v_cvt_pk_bf16_f32 v130, v126, v127
	v_cvt_pk_bf16_f32 v131, v128, v129
	s_nop 1
	v_cvt_pk_bf16_f32 v132, v122, v123
	v_cvt_pk_bf16_f32 v133, v124, v125
	global_store_dwordx4 v[136:137], v[130:133], off offset:256
	s_waitcnt vmcnt(16)
	s_branch .Lhs2_done

;     __device__ __forceinline__ float* out() const { return *(const __attribute__((address_space(4))) fptr_t*)(p + 256); }
; __device__ __forceinline__ void epi_res_norm(float* out, bf16_t* xn, const float* gain, float* slots, unsigned* cnt, bool fin, const f32x4 (&acc)[2][2][4][2], const Unit& u, int wr, int wc, int fr, int fq) {
;     ...
;         if (fr == 0 && fq == 0) __hip_atomic_fetch_add(cnt + 64 * u.pm, 1u, __ATOMIC_RELAXED, __HIP_MEMORY_SCOPE_AGENT);
;         if (!fin) epi_res(out, acc, u, wr, wc, fr, fq);
;         if (wr == 0 && wc == 0) {
;             const unsigned long long t0 = __builtin_amdgcn_s_memrealtime();
;             for (;;) {
;                 if ((unsigned)__builtin_amdgcn_readfirstlane(__hip_atomic_load(cnt + 64 * u.pm, __ATOMIC_RELAXED, __HIP_MEMORY_SCOPE_AGENT)) >= 32u) break;
;                 if (__builtin_amdgcn_s_memrealtime() - t0 > 2000000ull) break;
;                 __builtin_amdgcn_s_sleep(2);
;             }
.Lhs2_done:
	s_and_saveexec_b64 s[58:59], s[44:45]
	s_cbranch_execz .LBB0_285
	s_mov_b64 s[60:61], exec
	v_mbcnt_lo_u32_b32 v80, s60, 0
	v_mbcnt_hi_u32_b32 v80, s61, v80
	v_cmp_eq_u32_e32 vcc, 0, v80
	s_and_b64 s[22:23], exec, vcc
	s_mov_b64 exec, s[22:23]
	s_cbranch_execz .LBB0_285
	s_lshl_b32 s22, s88, 6
	s_ashr_i32 s23, s22, 31
	s_lshl_b64 s[22:23], s[22:23], 2
	s_add_u32 s22, s84, s22
	s_addc_u32 s23, s85, s23
	s_bcnt1_i32_b64 s57, s[60:61]
	v_mov_b32_e32 v80, s57
	global_atomic_add v81, v80, s[22:23]
.LBB0_285:
	s_or_b64 exec, exec, s[58:59]
.LBB0_287:
	s_andn2_b64 vcc, exec, s[16:17]
	s_cbranch_vccnz .LBB0_294
	s_memrealtime s[58:59]
	s_lshl_b32 s22, s88, 6
	s_ashr_i32 s23, s22, 31
	s_lshl_b64 s[22:23], s[22:23], 2
	s_add_u32 s60, s84, s22
	s_addc_u32 s61, s85, s23
	s_branch .LBB0_290
